# pair-scoped P1->P2 barrier + P1 tile order rotated per XCD pair (each pair starts at a different output section: epilogue kinds and store bursts differ across pairs, no idle stagger)
# speedup vs baseline: 1.0239x; 1.0239x over previous
;     __host__ __device__ bool next(int i, Unit& u) const {
;         const long L = (long)i * G + c; if (L >= nwg) return false;
;         int wgid = (int)L; { const int q = nwg / NXCD, r = nwg % NXCD, xcd = wgid % NXCD, off = wgid / NXCD; wgid = (xcd < r ? xcd * (q + 1) : r * (q + 1) + (xcd - r) * q) + off; }
;         const int nig = WGM * nN, gid = wgid / nig, fm = gid * WGM, gsz = (nM - fm) < WGM ? (nM - fm) : WGM;
;         u.pm = fm + ((wgid % nig) % gsz); u.pn = (wgid % nig) / gsz; return true;
; __global__ void __launch_bounds__(NWAVES * 64, 2) mk_fwd(Args a) {
;     ...
;             pg8::Unit u0; int pm0 = -1; if (S.next(0, u0)) pm0 = u0.pm;
.LBB0_151:
	s_ashr_i32 s2, s12, 3
	s_add_i32 s2, s17, s2
	s_ashr_i32 s3, s2, 31
	s_lshr_b32 s3, s3, 24
	s_add_i32 s3, s2, s3
	s_ashr_i32 s12, s3, 8
	s_and_b32 s3, s3, 0xff00
	s_sub_i32 s2, s2, s3
	s_sext_i32_i16 s3, s2
	s_bfe_u32 s3, s3, 0x3001c
	s_add_i32 s3, s2, s3
	s_sext_i32_i16 s16, s3
	s_and_b32 s3, s3, 0xfff8
	s_sub_i32 s2, s2, s3
	s_lshl_b32 s12, s12, 3
	s_sext_i32_i16 s2, s2
	s_add_i32 s52, s12, s2
	s_ashr_i32 s42, s16, 3
	s_cmp_lg_u32 s98, 0
	s_cbranch_scc0 .Lrot_skip0
	s_bfe_u32 s2, s1, 0x20001
	s_lshl_b32 s2, s2, 3
	s_add_i32 s42, s42, s2

;     __host__ __device__ bool next(int i, Unit& u) const {
;         const long L = (long)i * G + c; if (L >= nwg) return false;
;         int wgid = (int)L; { const int q = nwg / NXCD, r = nwg % NXCD, xcd = wgid % NXCD, off = wgid / NXCD; wgid = (xcd < r ? xcd * (q + 1) : r * (q + 1) + (xcd - r) * q) + off; }
;         const int nig = WGM * nN, gid = wgid / nig, fm = gid * WGM, gsz = (nM - fm) < WGM ? (nM - fm) : WGM;
;         u.pm = fm + ((wgid % nig) % gsz); u.pn = (wgid % nig) / gsz; return true;
; template <class Epi, class Sched, bool ALIGN_EPI = false, bool SP2 = false, bool SPLITK = false>
; __device__ __forceinline__ void gemm_phase(PG8_LAS unsigned char* lds, const Gemm g, const Sched& S, const Epi& E) {
;     ...
;         const bool has_next = S.next(ui + 1, nxt);
.LBB0_158:
	s_add_i32 s68, s68, 1
	s_mul_i32 s4, s68, s79
	s_mul_hi_u32 s12, s68, s80
	s_add_i32 s12, s12, s4
	s_mul_i32 s4, s68, s80
	s_add_u32 s36, s4, s1
	s_addc_u32 s37, s12, s13
	v_mov_b64_e32 v[2:3], 0x7ff
	v_cmp_gt_i64_e32 vcc, s[36:37], v[2:3]
	v_cmp_lt_i64_e64 s[38:39], s[36:37], v[236:237]
	s_cbranch_vccnz .LBB0_164
	s_cmp_lg_u32 s98, 0
	s_cbranch_scc0 .Lrot_skip1
	s_bfe_u32 s4, s1, 0x20001
	s_lshl_b32 s4, s4, 1
	s_add_i32 s4, s4, s68
	s_and_b32 s4, s4, 7
	s_mul_i32 s4, s4, s80
	s_add_i32 s36, s4, s1
